# band-tile causal/window masks: one scalar-selected edge per (wave, tile), one inline-constant compare + one select per element (was per-element branchy code)
# speedup vs baseline: 1.0167x; 1.0167x over previous
; #define WAIT_BAR(N) asm volatile("s_waitcnt vmcnt(" #N ") lgkmcnt(0)\n\ts_barrier":::"memory")
;   #define DMA_K(t,slot) glds16(ksrc+(long)(t)*KVBLK*PIN,(unsigned)__builtin_amdgcn_readfirstlane(kdst+(slot)))
;   #define CINIT(C0,C1,btl) do{ const float b_=(btl); _Pragma("unroll") for(int r=0;r<16;++r){ C0[r]=__builtin_fmaf(s2,(float)((r&3)+8*(r>>2)),b_); C1[r]=__builtin_fmaf(s2,(float)((r&3)+8*(r>>2)+32),b_);} }while(0)
;   #define CMASK(P0,P1,t) do{ if(WIN||(t)>=NT-4)gmask(P0,P1,64*(t),qrel,hi,WIN);}while(0)
;   #define CMASK(P0,P1,t) do{}while(0)
;   #define CMASK(P0,P1,t) do{ if(WIN||(t)>=NT-4)gmask(P0,P1,64*(t),qrel,hi,WIN);}while(0)
; __device__ __forceinline__ void gmask(f32x16&p0,f32x16&p1,int kvb,int qrel,int hi,bool WIN){
;   const float NEG=-INFINITY; int kb=kvb+4*hi;
;   #pragma unroll
;   for(int r=0;r<16;++r){int kv=kb+(r&3)+8*(r>>2); if(kv>qrel)p0[r]=NEG; if(kv+32>qrel)p1[r]=NEG;
;     if(WIN){ if(kv<=qrel-128)p0[r]=NEG; if(kv+32<=qrel-128)p1[r]=NEG; } }
; }
; template<int THRL> __device__ __forceinline__ void attn_unit(long rowbase,int qb,int t0,bool WIN,bool NOMAX,const bf16*Qc,const bf16*__restrict__ Kc,const bf16*__restrict__ Vc,bf16*Oc,float s2,float sink2,char*shm,
;     bf16x8 (&qr)[4],bool pref,const bf16*qkvb,int vn,int in_){
;     ...
;   const int qrel=q0-t0*KVBLK+wid*QBLK+r32;
;   const float qb2=s2*(float)(qrel-4*hi);
;     ...
;   bool resc=false;
;     ...
;   f32x16 pA0,pA1,pB0,pB1;
;   int sl_prev=0,sl_cur=0,sl_next=SLOTB;
;     ...
;   if(!pref){ DMA_K(2,2*SLOTB);
;     WAIT_BAR(3); }
;   else { WAIT_BAR(5); }
;   CINIT(pA0,pA1,-qb2); qkt(pA0,pA1,Kbase,qr,r32,hi);asm volatile("s_nop 15\n\ts_nop 7":"+v"(pA0),"+v"(pA1));CMASK(pA0,pA1,0);
.LBB0_265:
	s_sub_i32 s38, s4, s45
	v_or_b32_e32 v18, s38, v180
	v_lshlrev_b32_e32 v230, 2, v181
	v_add_u32_e32 v223, s2, v18
	v_sub_u32_e32 v18, v223, v230
	v_cvt_f32_i32_e32 v19, v18
	v_lshlrev_b32_e32 v18, 10, v181
	v_lshlrev_b32_e32 v20, 4, v180
	v_add3_u32 v231, 0, v18, v20
	v_mul_f32_e32 v184, 0x3fb8aa3b, v34
	ds_read_b128 v[34:37], v231
	ds_read_b128 v[52:55], v231 offset:512
	v_mul_f32_e64 v186, v184, -v19
	v_fma_f32 v18, 0, v184, v186
	v_fma_f32 v19, v184, -v19, v184
	v_pk_fma_f32 v[20:21], v[184:185], s[8:9], v[186:187] op_sel_hi:[0,1,0]
	v_pk_fma_f32 v[22:23], v[184:185], s[10:11], v[186:187] op_sel_hi:[0,1,0]
	v_pk_fma_f32 v[24:25], v[184:185], s[12:13], v[186:187] op_sel_hi:[0,1,0]
	v_pk_fma_f32 v[26:27], v[184:185], s[14:15], v[186:187] op_sel_hi:[0,1,0]
	v_pk_fma_f32 v[28:29], v[184:185], s[16:17], v[186:187] op_sel_hi:[0,1,0]
	v_pk_fma_f32 v[30:31], v[184:185], s[18:19], v[186:187] op_sel_hi:[0,1,0]
	v_pk_fma_f32 v[32:33], v[184:185], s[20:21], v[186:187] op_sel_hi:[0,1,0]
	v_pk_fma_f32 v[48:49], v[184:185], s[22:23], v[186:187] op_sel_hi:[0,1,0]
	v_pk_fma_f32 v[46:47], v[184:185], s[24:25], v[186:187] op_sel_hi:[0,1,0]
	s_waitcnt vmcnt(3) lgkmcnt(1)
	v_mfma_f32_32x32x16_bf16 v[18:33], v[34:37], v[2:5], v[18:33]
	v_fma_f32 v44, v184, s26, v186
	v_fma_f32 v45, v184, s27, v186
	v_fma_f32 v42, v184, s28, v186
	v_fma_f32 v43, v184, s29, v186
	v_fma_f32 v40, v184, s30, v186
	v_fma_f32 v41, v184, s31, v186
	v_pk_fma_f32 v[38:39], v[184:185], s[34:35], v[186:187] op_sel_hi:[0,1,0]
	v_pk_fma_f32 v[36:37], v[184:185], s[36:37], v[186:187] op_sel_hi:[0,1,0]
	v_pk_fma_f32 v[34:35], v[184:185], s[92:93], v[186:187] op_sel_hi:[0,1,0]
	s_addk_i32 s4, 0x100
	s_lshr_b32 s4, s4, 6
	s_waitcnt lgkmcnt(0)
	v_mfma_f32_32x32x16_bf16 v[34:49], v[52:55], v[2:5], v[34:49]
	ds_read_b128 v[52:55], v231 offset:2048
	s_sub_i32 s4, s4, s48
	s_cmp_lt_i32 s4, 5
	s_cselect_b64 s[38:39], -1, 0
	s_or_b64 s[38:39], s[62:63], s[38:39]
	s_andn2_b64 vcc, exec, s[38:39]
	v_add_u32_e32 v224, 0xffffff80, v223
	s_waitcnt vmcnt(2) lgkmcnt(0)
	v_mfma_f32_32x32x16_bf16 v[18:33], v[52:55], v[6:9], v[18:33]
	ds_read_b128 v[52:55], v231 offset:2560
	s_waitcnt lgkmcnt(0)
	v_mfma_f32_32x32x16_bf16 v[34:49], v[52:55], v[6:9], v[34:49]
	ds_read_b128 v[52:55], v231 offset:4096
	s_waitcnt vmcnt(1) lgkmcnt(0)
	v_mfma_f32_32x32x16_bf16 v[18:33], v[52:55], v[10:13], v[18:33]
	ds_read_b128 v[52:55], v231 offset:4608
	s_waitcnt lgkmcnt(0)
	v_mfma_f32_32x32x16_bf16 v[34:49], v[52:55], v[10:13], v[34:49]
	ds_read_b128 v[52:55], v231 offset:6144
	s_waitcnt vmcnt(0) lgkmcnt(0)
	v_mfma_f32_32x32x16_bf16 v[18:33], v[52:55], v[14:17], v[18:33]
	ds_read_b128 v[52:55], v231 offset:6656
	s_waitcnt lgkmcnt(0)
	v_mfma_f32_32x32x16_bf16 v[34:49], v[52:55], v[14:17], v[34:49]
	v_cndmask_b32_e64 v52, 0, 1, s[62:63]
	v_cmp_ne_u32_e64 s[38:39], 1, v52
	s_nop 15
	s_nop 7
	s_cbranch_vccnz .LBB0_330
	v_sub_u32_e32 v52, v223, v230
	s_nop 0
	v_readfirstlane_b32 s40, v52
	s_cmp_gt_i32 s40, 66
	s_cbranch_scc1 .Lmy_mk_c_s0
	v_cmp_le_i32_e32 vcc, 0, v52
	v_cndmask_b32_e32 v18, v217, v18, vcc
	v_cmp_le_i32_e32 vcc, 32, v52
	v_cndmask_b32_e32 v34, v217, v34, vcc
	v_cmp_le_i32_e32 vcc, 1, v52
	v_cndmask_b32_e32 v19, v217, v19, vcc
	v_cmp_le_i32_e32 vcc, 33, v52
	v_cndmask_b32_e32 v35, v217, v35, vcc
	v_cmp_le_i32_e32 vcc, 2, v52
	v_cndmask_b32_e32 v20, v217, v20, vcc
	v_cmp_le_i32_e32 vcc, 34, v52
	v_cndmask_b32_e32 v36, v217, v36, vcc
	v_cmp_le_i32_e32 vcc, 3, v52
	v_cndmask_b32_e32 v21, v217, v21, vcc
	v_cmp_le_i32_e32 vcc, 35, v52
	v_cndmask_b32_e32 v37, v217, v37, vcc
	v_cmp_le_i32_e32 vcc, 8, v52
	v_cndmask_b32_e32 v22, v217, v22, vcc
	v_cmp_le_i32_e32 vcc, 40, v52
	v_cndmask_b32_e32 v38, v217, v38, vcc
	v_cmp_le_i32_e32 vcc, 9, v52
	v_cndmask_b32_e32 v23, v217, v23, vcc
	v_cmp_le_i32_e32 vcc, 41, v52
	v_cndmask_b32_e32 v39, v217, v39, vcc
	v_cmp_le_i32_e32 vcc, 10, v52
	v_cndmask_b32_e32 v24, v217, v24, vcc
	v_cmp_le_i32_e32 vcc, 42, v52
	v_cndmask_b32_e32 v40, v217, v40, vcc
	v_cmp_le_i32_e32 vcc, 11, v52
	v_cndmask_b32_e32 v25, v217, v25, vcc
	v_cmp_le_i32_e32 vcc, 43, v52
	v_cndmask_b32_e32 v41, v217, v41, vcc
	v_cmp_le_i32_e32 vcc, 16, v52
	v_cndmask_b32_e32 v26, v217, v26, vcc
	v_cmp_le_i32_e32 vcc, 48, v52
	v_cndmask_b32_e32 v42, v217, v42, vcc
	v_cmp_le_i32_e32 vcc, 17, v52
	v_cndmask_b32_e32 v27, v217, v27, vcc
	v_cmp_le_i32_e32 vcc, 49, v52
	v_cndmask_b32_e32 v43, v217, v43, vcc
	v_cmp_le_i32_e32 vcc, 18, v52
	v_cndmask_b32_e32 v28, v217, v28, vcc
	v_cmp_le_i32_e32 vcc, 50, v52
	v_cndmask_b32_e32 v44, v217, v44, vcc
	v_cmp_le_i32_e32 vcc, 19, v52
	v_cndmask_b32_e32 v29, v217, v29, vcc
	v_cmp_le_i32_e32 vcc, 51, v52
	v_cndmask_b32_e32 v45, v217, v45, vcc
	v_cmp_le_i32_e32 vcc, 24, v52
	v_cndmask_b32_e32 v30, v217, v30, vcc
	v_cmp_le_i32_e32 vcc, 56, v52
	v_cndmask_b32_e32 v46, v217, v46, vcc
	v_cmp_le_i32_e32 vcc, 25, v52
	v_cndmask_b32_e32 v31, v217, v31, vcc
	v_cmp_le_i32_e32 vcc, 57, v52
	v_cndmask_b32_e32 v47, v217, v47, vcc
	v_cmp_le_i32_e32 vcc, 26, v52
	v_cndmask_b32_e32 v32, v217, v32, vcc
	v_cmp_le_i32_e32 vcc, 58, v52
	v_cndmask_b32_e32 v48, v217, v48, vcc
	v_cmp_le_i32_e32 vcc, 27, v52
	v_cndmask_b32_e32 v33, v217, v33, vcc
	v_cmp_le_i32_e32 vcc, 59, v52
	v_cndmask_b32_e32 v49, v217, v49, vcc
; __device__ __forceinline__ void gmask(f32x16&p0,f32x16&p1,int kvb,int qrel,int hi,bool WIN){
;   const float NEG=-INFINITY; int kb=kvb+4*hi;
;   #pragma unroll
;   for(int r=0;r<16;++r){int kv=kb+(r&3)+8*(r>>2); if(kv>qrel)p0[r]=NEG; if(kv+32>qrel)p1[r]=NEG;
;     if(WIN){ if(kv<=qrel-128)p0[r]=NEG; if(kv+32<=qrel-128)p1[r]=NEG; } }
; }
.Lmy_mk_c_s0:
	s_and_b64 vcc, exec, s[38:39]
	s_cbranch_vccnz .Lmy_mk_e_s0
	s_cmp_lt_i32 s40, 0x61
	s_cbranch_scc1 .Lmy_mk_e_s0
	v_add_u32_e32 v53, 0xffffff81, v52
	v_cmp_ge_i32_e32 vcc, 0, v53
	v_cndmask_b32_e32 v18, v217, v18, vcc
	v_cmp_ge_i32_e32 vcc, 32, v53
	v_cndmask_b32_e32 v34, v217, v34, vcc
	v_cmp_ge_i32_e32 vcc, 1, v53
	v_cndmask_b32_e32 v19, v217, v19, vcc
	v_cmp_ge_i32_e32 vcc, 33, v53
	v_cndmask_b32_e32 v35, v217, v35, vcc
	v_cmp_ge_i32_e32 vcc, 2, v53
	v_cndmask_b32_e32 v20, v217, v20, vcc
	v_cmp_ge_i32_e32 vcc, 34, v53
	v_cndmask_b32_e32 v36, v217, v36, vcc
	v_cmp_ge_i32_e32 vcc, 3, v53
	v_cndmask_b32_e32 v21, v217, v21, vcc
	v_cmp_ge_i32_e32 vcc, 35, v53
	v_cndmask_b32_e32 v37, v217, v37, vcc
	v_cmp_ge_i32_e32 vcc, 8, v53
	v_cndmask_b32_e32 v22, v217, v22, vcc
	v_cmp_ge_i32_e32 vcc, 40, v53
	v_cndmask_b32_e32 v38, v217, v38, vcc
	v_cmp_ge_i32_e32 vcc, 9, v53
	v_cndmask_b32_e32 v23, v217, v23, vcc
	v_cmp_ge_i32_e32 vcc, 41, v53
	v_cndmask_b32_e32 v39, v217, v39, vcc
	v_cmp_ge_i32_e32 vcc, 10, v53
	v_cndmask_b32_e32 v24, v217, v24, vcc
	v_cmp_ge_i32_e32 vcc, 42, v53
	v_cndmask_b32_e32 v40, v217, v40, vcc
	v_cmp_ge_i32_e32 vcc, 11, v53
	v_cndmask_b32_e32 v25, v217, v25, vcc
	v_cmp_ge_i32_e32 vcc, 43, v53
	v_cndmask_b32_e32 v41, v217, v41, vcc
	v_cmp_ge_i32_e32 vcc, 16, v53
	v_cndmask_b32_e32 v26, v217, v26, vcc
	v_cmp_ge_i32_e32 vcc, 48, v53
	v_cndmask_b32_e32 v42, v217, v42, vcc
	v_cmp_ge_i32_e32 vcc, 17, v53
	v_cndmask_b32_e32 v27, v217, v27, vcc
	v_cmp_ge_i32_e32 vcc, 49, v53
	v_cndmask_b32_e32 v43, v217, v43, vcc
	v_cmp_ge_i32_e32 vcc, 18, v53
	v_cndmask_b32_e32 v28, v217, v28, vcc
	v_cmp_ge_i32_e32 vcc, 50, v53
	v_cndmask_b32_e32 v44, v217, v44, vcc
	v_cmp_ge_i32_e32 vcc, 19, v53
	v_cndmask_b32_e32 v29, v217, v29, vcc
	v_cmp_ge_i32_e32 vcc, 51, v53
	v_cndmask_b32_e32 v45, v217, v45, vcc
	v_cmp_ge_i32_e32 vcc, 24, v53
	v_cndmask_b32_e32 v30, v217, v30, vcc
	v_cmp_ge_i32_e32 vcc, 56, v53
	v_cndmask_b32_e32 v46, v217, v46, vcc
	v_cmp_ge_i32_e32 vcc, 25, v53
	v_cndmask_b32_e32 v31, v217, v31, vcc
	v_cmp_ge_i32_e32 vcc, 57, v53
	v_cndmask_b32_e32 v47, v217, v47, vcc
	v_cmp_ge_i32_e32 vcc, 26, v53
	v_cndmask_b32_e32 v32, v217, v32, vcc
	v_cmp_ge_i32_e32 vcc, 58, v53
	v_cndmask_b32_e32 v48, v217, v48, vcc
	v_cmp_ge_i32_e32 vcc, 27, v53
	v_cndmask_b32_e32 v33, v217, v33, vcc
	v_cmp_ge_i32_e32 vcc, 59, v53
	v_cndmask_b32_e32 v49, v217, v49, vcc
.Lmy_mk_e_s0:
.LBB0_330:
	v_mov_b32_e32 v190, v184
	v_mov_b32_e32 v191, v184
	v_mov_b32_e32 v188, v184
	v_mov_b32_e32 v189, v184
	v_cmp_nge_f32_e64 s[40:41], s34, v51
	v_mov_b32_e32 v225, 0
	s_and_saveexec_b64 s[42:43], s[40:41]
	s_cbranch_execz .LBB0_332
	v_max3_f32 v51, v18, v19, v34
	v_max3_f32 v52, v20, v21, v35
	s_nop 0
	v_max3_f32 v51, v51, v36, v37
	v_max3_f32 v52, v52, v24, v25
	s_nop 0
	v_max3_f32 v51, v51, v22, v23
	v_max3_f32 v52, v52, v40, v41
	s_nop 0
	v_max3_f32 v51, v51, v38, v39
	v_max3_f32 v52, v52, v28, v29
	s_nop 0
	v_max3_f32 v51, v51, v26, v27
	v_max3_f32 v52, v52, v44, v45
	s_nop 0
	v_max3_f32 v51, v51, v42, v43
	v_max3_f32 v52, v52, v32, v33
	s_nop 0
	v_max3_f32 v51, v51, v30, v31
	v_max3_f32 v52, v52, v48, v49
	s_nop 0
	v_max3_f32 v51, v51, v46, v47
	s_nop 0
	v_max_f32_e32 v51, v51, v52
	s_nop 0
	v_mov_b32_e32 v52, v51
	s_nop 1
	v_permlane32_swap_b32_e32 v51, v52
	v_max_f32_e32 v51, v51, v52
	s_nop 0
	v_max_f32_e32 v51, v51, v51
	v_max_f32_e32 v51, 0, v51
	v_add_f32_e32 v225, v1, v51
	v_sub_f32_e32 v18, v18, v51
	v_sub_f32_e32 v34, v34, v51
	v_sub_f32_e32 v19, v19, v51
	v_sub_f32_e32 v35, v35, v51
	v_sub_f32_e32 v20, v20, v51
	v_sub_f32_e32 v36, v36, v51
	v_sub_f32_e32 v21, v21, v51
	v_sub_f32_e32 v37, v37, v51
	v_sub_f32_e32 v22, v22, v51
	v_sub_f32_e32 v38, v38, v51
	v_sub_f32_e32 v23, v23, v51
	v_sub_f32_e32 v39, v39, v51
	v_sub_f32_e32 v24, v24, v51
	v_sub_f32_e32 v40, v40, v51
	v_sub_f32_e32 v25, v25, v51
	v_sub_f32_e32 v41, v41, v51
	v_sub_f32_e32 v26, v26, v51
	v_sub_f32_e32 v42, v42, v51
	v_sub_f32_e32 v27, v27, v51
	v_sub_f32_e32 v43, v43, v51
	v_sub_f32_e32 v28, v28, v51
	v_sub_f32_e32 v44, v44, v51
	v_sub_f32_e32 v29, v29, v51
	v_sub_f32_e32 v45, v45, v51
	v_sub_f32_e32 v30, v30, v51
	v_sub_f32_e32 v46, v46, v51
	v_sub_f32_e32 v31, v31, v51
	v_sub_f32_e32 v47, v47, v51
	v_sub_f32_e32 v32, v32, v51
	v_sub_f32_e32 v48, v48, v51
	v_sub_f32_e32 v33, v33, v51
	v_sub_f32_e32 v49, v49, v51

; __device__ __forceinline__ void gmask(f32x16&p0,f32x16&p1,int kvb,int qrel,int hi,bool WIN){
;   const float NEG=-INFINITY; int kb=kvb+4*hi;
;   #pragma unroll
;   for(int r=0;r<16;++r){int kv=kb+(r&3)+8*(r>>2); if(kv>qrel)p0[r]=NEG; if(kv+32>qrel)p1[r]=NEG;
;     if(WIN){ if(kv<=qrel-128)p0[r]=NEG; if(kv+32<=qrel-128)p1[r]=NEG; } }
; }
.LBB0_362:
	s_add_i32 s68, s70, -2
	s_add_i32 s44, s87, s79
	s_mov_b32 s45, m0
	s_mov_b32 m0, s44
	s_nop 0
	global_load_lds_dwordx4 v[192:193], off
	s_add_i32 m0, s44, 0xe780
	s_nop 0
	global_load_lds_dwordx4 v[192:193], off offset:128
	s_mov_b32 m0, s45
	s_cmp_ge_i32 s68, s48
	s_cselect_b64 s[44:45], -1, 0
	s_or_b64 s[44:45], s[62:63], s[44:45]
	s_andn2_b64 vcc, exec, s[44:45]
	v_add_u32_e32 v83, s49, v230
	s_cbranch_vccnz .LBB0_427
	v_sub_u32_e32 v109, v223, v83
	v_add_u32_e32 v109, 0x80, v109
	s_nop 0
	v_readfirstlane_b32 s44, v109
	s_cmp_gt_i32 s44, 66
	s_cbranch_scc1 .Lmy_mk_c_b1
	v_cmp_le_i32_e32 vcc, 0, v109
	v_cndmask_b32_e32 v66, v217, v66, vcc
	v_cmp_le_i32_e32 vcc, 32, v109
	v_cndmask_b32_e32 v50, v217, v50, vcc
	v_cmp_le_i32_e32 vcc, 1, v109
	v_cndmask_b32_e32 v67, v217, v67, vcc
	v_cmp_le_i32_e32 vcc, 33, v109
	v_cndmask_b32_e32 v51, v217, v51, vcc
	v_cmp_le_i32_e32 vcc, 2, v109
	v_cndmask_b32_e32 v68, v217, v68, vcc
	v_cmp_le_i32_e32 vcc, 34, v109
	v_cndmask_b32_e32 v52, v217, v52, vcc
	v_cmp_le_i32_e32 vcc, 3, v109
	v_cndmask_b32_e32 v69, v217, v69, vcc
	v_cmp_le_i32_e32 vcc, 35, v109
	v_cndmask_b32_e32 v53, v217, v53, vcc
	v_cmp_le_i32_e32 vcc, 8, v109
	v_cndmask_b32_e32 v70, v217, v70, vcc
	v_cmp_le_i32_e32 vcc, 40, v109
	v_cndmask_b32_e32 v54, v217, v54, vcc
	v_cmp_le_i32_e32 vcc, 9, v109
	v_cndmask_b32_e32 v71, v217, v71, vcc
	v_cmp_le_i32_e32 vcc, 41, v109
	v_cndmask_b32_e32 v55, v217, v55, vcc
	v_cmp_le_i32_e32 vcc, 10, v109
	v_cndmask_b32_e32 v72, v217, v72, vcc
	v_cmp_le_i32_e32 vcc, 42, v109
	v_cndmask_b32_e32 v56, v217, v56, vcc
	v_cmp_le_i32_e32 vcc, 11, v109
	v_cndmask_b32_e32 v73, v217, v73, vcc
	v_cmp_le_i32_e32 vcc, 43, v109
	v_cndmask_b32_e32 v57, v217, v57, vcc
	v_cmp_le_i32_e32 vcc, 16, v109
	v_cndmask_b32_e32 v74, v217, v74, vcc
	v_cmp_le_i32_e32 vcc, 48, v109
	v_cndmask_b32_e32 v58, v217, v58, vcc
	v_cmp_le_i32_e32 vcc, 17, v109
	v_cndmask_b32_e32 v75, v217, v75, vcc
	v_cmp_le_i32_e32 vcc, 49, v109
	v_cndmask_b32_e32 v59, v217, v59, vcc
	v_cmp_le_i32_e32 vcc, 18, v109
	v_cndmask_b32_e32 v76, v217, v76, vcc
	v_cmp_le_i32_e32 vcc, 50, v109
	v_cndmask_b32_e32 v60, v217, v60, vcc
	v_cmp_le_i32_e32 vcc, 19, v109
	v_cndmask_b32_e32 v77, v217, v77, vcc
	v_cmp_le_i32_e32 vcc, 51, v109
	v_cndmask_b32_e32 v61, v217, v61, vcc
	v_cmp_le_i32_e32 vcc, 24, v109
	v_cndmask_b32_e32 v78, v217, v78, vcc
	v_cmp_le_i32_e32 vcc, 56, v109
	v_cndmask_b32_e32 v62, v217, v62, vcc
	v_cmp_le_i32_e32 vcc, 25, v109
	v_cndmask_b32_e32 v79, v217, v79, vcc
	v_cmp_le_i32_e32 vcc, 57, v109
	v_cndmask_b32_e32 v63, v217, v63, vcc
	v_cmp_le_i32_e32 vcc, 26, v109
	v_cndmask_b32_e32 v80, v217, v80, vcc
	v_cmp_le_i32_e32 vcc, 58, v109
	v_cndmask_b32_e32 v64, v217, v64, vcc
	v_cmp_le_i32_e32 vcc, 27, v109
	v_cndmask_b32_e32 v81, v217, v81, vcc
	v_cmp_le_i32_e32 vcc, 59, v109
	v_cndmask_b32_e32 v65, v217, v65, vcc
.Lmy_mk_c_b1:
	s_and_b64 vcc, exec, s[38:39]
	s_cbranch_vccnz .Lmy_mk_e_b1
	s_cmp_lt_i32 s44, 0x61
	s_cbranch_scc1 .Lmy_mk_e_b1
	v_add_u32_e32 v110, 0xffffff81, v109
	v_cmp_ge_i32_e32 vcc, 0, v110
	v_cndmask_b32_e32 v66, v217, v66, vcc
	v_cmp_ge_i32_e32 vcc, 32, v110
	v_cndmask_b32_e32 v50, v217, v50, vcc
	v_cmp_ge_i32_e32 vcc, 1, v110
	v_cndmask_b32_e32 v67, v217, v67, vcc
	v_cmp_ge_i32_e32 vcc, 33, v110
	v_cndmask_b32_e32 v51, v217, v51, vcc
	v_cmp_ge_i32_e32 vcc, 2, v110
	v_cndmask_b32_e32 v68, v217, v68, vcc
	v_cmp_ge_i32_e32 vcc, 34, v110
	v_cndmask_b32_e32 v52, v217, v52, vcc
	v_cmp_ge_i32_e32 vcc, 3, v110
	v_cndmask_b32_e32 v69, v217, v69, vcc
	v_cmp_ge_i32_e32 vcc, 35, v110
	v_cndmask_b32_e32 v53, v217, v53, vcc
	v_cmp_ge_i32_e32 vcc, 8, v110
	v_cndmask_b32_e32 v70, v217, v70, vcc
	v_cmp_ge_i32_e32 vcc, 40, v110
	v_cndmask_b32_e32 v54, v217, v54, vcc
	v_cmp_ge_i32_e32 vcc, 9, v110
	v_cndmask_b32_e32 v71, v217, v71, vcc
	v_cmp_ge_i32_e32 vcc, 41, v110
	v_cndmask_b32_e32 v55, v217, v55, vcc
	v_cmp_ge_i32_e32 vcc, 10, v110
	v_cndmask_b32_e32 v72, v217, v72, vcc
	v_cmp_ge_i32_e32 vcc, 42, v110
	v_cndmask_b32_e32 v56, v217, v56, vcc
	v_cmp_ge_i32_e32 vcc, 11, v110
	v_cndmask_b32_e32 v73, v217, v73, vcc
	v_cmp_ge_i32_e32 vcc, 43, v110
	v_cndmask_b32_e32 v57, v217, v57, vcc
	v_cmp_ge_i32_e32 vcc, 16, v110
	v_cndmask_b32_e32 v74, v217, v74, vcc
	v_cmp_ge_i32_e32 vcc, 48, v110
	v_cndmask_b32_e32 v58, v217, v58, vcc
	v_cmp_ge_i32_e32 vcc, 17, v110
	v_cndmask_b32_e32 v75, v217, v75, vcc
	v_cmp_ge_i32_e32 vcc, 49, v110
	v_cndmask_b32_e32 v59, v217, v59, vcc
	v_cmp_ge_i32_e32 vcc, 18, v110
	v_cndmask_b32_e32 v76, v217, v76, vcc
	v_cmp_ge_i32_e32 vcc, 50, v110
	v_cndmask_b32_e32 v60, v217, v60, vcc
	v_cmp_ge_i32_e32 vcc, 19, v110
	v_cndmask_b32_e32 v77, v217, v77, vcc
	v_cmp_ge_i32_e32 vcc, 51, v110
	v_cndmask_b32_e32 v61, v217, v61, vcc
	v_cmp_ge_i32_e32 vcc, 24, v110
	v_cndmask_b32_e32 v78, v217, v78, vcc
	v_cmp_ge_i32_e32 vcc, 56, v110
	v_cndmask_b32_e32 v62, v217, v62, vcc
	v_cmp_ge_i32_e32 vcc, 25, v110
	v_cndmask_b32_e32 v79, v217, v79, vcc
	v_cmp_ge_i32_e32 vcc, 57, v110
	v_cndmask_b32_e32 v63, v217, v63, vcc
	v_cmp_ge_i32_e32 vcc, 26, v110
	v_cndmask_b32_e32 v80, v217, v80, vcc
	v_cmp_ge_i32_e32 vcc, 58, v110
	v_cndmask_b32_e32 v64, v217, v64, vcc
	v_cmp_ge_i32_e32 vcc, 27, v110
	v_cndmask_b32_e32 v81, v217, v81, vcc
	v_cmp_ge_i32_e32 vcc, 59, v110
	v_cndmask_b32_e32 v65, v217, v65, vcc
.Lmy_mk_e_b1:
.LBB0_427:
	v_add_f32_e32 v82, v82, v108
	s_mov_b64 s[44:45], 0
	s_and_saveexec_b64 s[66:67], s[40:41]
	s_cbranch_execz .LBB0_430
	v_max_f32_e32 v108, v67, v67
	v_max_f32_e32 v109, v66, v66
	v_max_f32_e32 v108, v109, v108
	v_max3_f32 v109, v68, v69, v51
	v_max3_f32 v108, v108, v50, v52
	v_max3_f32 v108, v108, v53, v70
	v_max3_f32 v109, v109, v72, v73
	v_max3_f32 v108, v108, v71, v54
	v_max3_f32 v109, v109, v56, v57
	v_max3_f32 v108, v108, v55, v74
	v_max3_f32 v109, v109, v76, v77
	v_max3_f32 v108, v108, v75, v58
	v_max3_f32 v109, v109, v60, v61
	v_max3_f32 v108, v108, v59, v78
	v_max3_f32 v109, v109, v80, v81
	v_max3_f32 v108, v108, v79, v62
	v_max3_f32 v109, v109, v64, v65
	v_max3_f32 v108, v108, v63, v109
	v_mov_b32_e32 v109, v108
	s_nop 1
	v_permlane32_swap_b32_e32 v108, v109
	v_max_f32_e32 v109, v109, v109
	v_max_f32_e32 v108, v108, v108
	v_max_f32_e32 v108, v108, v109
	v_cmp_lt_f32_e32 vcc, s84, v108
	s_cbranch_vccnz .LBB0_532

; __device__ __forceinline__ void gmask(f32x16&p0,f32x16&p1,int kvb,int qrel,int hi,bool WIN){
;   const float NEG=-INFINITY; int kb=kvb+4*hi;
;   #pragma unroll
;   for(int r=0;r<16;++r){int kv=kb+(r&3)+8*(r>>2); if(kv>qrel)p0[r]=NEG; if(kv+32>qrel)p1[r]=NEG;
;     if(WIN){ if(kv<=qrel-128)p0[r]=NEG; if(kv+32<=qrel-128)p1[r]=NEG; } }
; }
.LBB0_438:
	s_add_i32 s44, s70, -1
	s_cmp_ge_i32 s44, s48
	s_cselect_b64 s[44:45], -1, 0
	s_or_b64 s[44:45], s[62:63], s[44:45]
	s_andn2_b64 vcc, exec, s[44:45]
	s_cbranch_vccnz .LBB0_503
	v_sub_u32_e32 v59, v223, v83
	v_add_u32_e32 v59, 64, v59
	s_nop 0
	v_readfirstlane_b32 s44, v59
	s_cmp_gt_i32 s44, 66
	s_cbranch_scc1 .Lmy_mk_c_b2
	v_cmp_le_i32_e32 vcc, 0, v59
	v_cndmask_b32_e32 v114, v217, v114, vcc
	v_cmp_le_i32_e32 vcc, 32, v59
	v_cndmask_b32_e32 v98, v217, v98, vcc
	v_cmp_le_i32_e32 vcc, 1, v59
	v_cndmask_b32_e32 v115, v217, v115, vcc
	v_cmp_le_i32_e32 vcc, 33, v59
	v_cndmask_b32_e32 v99, v217, v99, vcc
	v_cmp_le_i32_e32 vcc, 2, v59
	v_cndmask_b32_e32 v116, v217, v116, vcc
	v_cmp_le_i32_e32 vcc, 34, v59
	v_cndmask_b32_e32 v100, v217, v100, vcc
	v_cmp_le_i32_e32 vcc, 3, v59
	v_cndmask_b32_e32 v117, v217, v117, vcc
	v_cmp_le_i32_e32 vcc, 35, v59
	v_cndmask_b32_e32 v101, v217, v101, vcc
	v_cmp_le_i32_e32 vcc, 8, v59
	v_cndmask_b32_e32 v118, v217, v118, vcc
	v_cmp_le_i32_e32 vcc, 40, v59
	v_cndmask_b32_e32 v102, v217, v102, vcc
	v_cmp_le_i32_e32 vcc, 9, v59
	v_cndmask_b32_e32 v119, v217, v119, vcc
	v_cmp_le_i32_e32 vcc, 41, v59
	v_cndmask_b32_e32 v103, v217, v103, vcc
	v_cmp_le_i32_e32 vcc, 10, v59
	v_cndmask_b32_e32 v120, v217, v120, vcc
	v_cmp_le_i32_e32 vcc, 42, v59
	v_cndmask_b32_e32 v104, v217, v104, vcc
	v_cmp_le_i32_e32 vcc, 11, v59
	v_cndmask_b32_e32 v121, v217, v121, vcc
	v_cmp_le_i32_e32 vcc, 43, v59
	v_cndmask_b32_e32 v105, v217, v105, vcc
	v_cmp_le_i32_e32 vcc, 16, v59
	v_cndmask_b32_e32 v122, v217, v122, vcc
	v_cmp_le_i32_e32 vcc, 48, v59
	v_cndmask_b32_e32 v106, v217, v106, vcc
	v_cmp_le_i32_e32 vcc, 17, v59
	v_cndmask_b32_e32 v123, v217, v123, vcc
	v_cmp_le_i32_e32 vcc, 49, v59
	v_cndmask_b32_e32 v107, v217, v107, vcc
	v_cmp_le_i32_e32 vcc, 18, v59
	v_cndmask_b32_e32 v124, v217, v124, vcc
	v_cmp_le_i32_e32 vcc, 50, v59
	v_cndmask_b32_e32 v108, v217, v108, vcc
	v_cmp_le_i32_e32 vcc, 19, v59
	v_cndmask_b32_e32 v125, v217, v125, vcc
	v_cmp_le_i32_e32 vcc, 51, v59
	v_cndmask_b32_e32 v109, v217, v109, vcc
	v_cmp_le_i32_e32 vcc, 24, v59
	v_cndmask_b32_e32 v126, v217, v126, vcc
	v_cmp_le_i32_e32 vcc, 56, v59
	v_cndmask_b32_e32 v110, v217, v110, vcc
	v_cmp_le_i32_e32 vcc, 25, v59
	v_cndmask_b32_e32 v127, v217, v127, vcc
	v_cmp_le_i32_e32 vcc, 57, v59
	v_cndmask_b32_e32 v111, v217, v111, vcc
	v_cmp_le_i32_e32 vcc, 26, v59
	v_cndmask_b32_e32 v128, v217, v128, vcc
	v_cmp_le_i32_e32 vcc, 58, v59
	v_cndmask_b32_e32 v112, v217, v112, vcc
	v_cmp_le_i32_e32 vcc, 27, v59
	v_cndmask_b32_e32 v129, v217, v129, vcc
	v_cmp_le_i32_e32 vcc, 59, v59
	v_cndmask_b32_e32 v113, v217, v113, vcc
.Lmy_mk_c_b2:
	s_and_b64 vcc, exec, s[38:39]
	s_cbranch_vccnz .Lmy_mk_e_b2
	s_cmp_lt_i32 s44, 0x61
	s_cbranch_scc1 .Lmy_mk_e_b2
	v_add_u32_e32 v60, 0xffffff81, v59
	v_cmp_ge_i32_e32 vcc, 0, v60
	v_cndmask_b32_e32 v114, v217, v114, vcc
	v_cmp_ge_i32_e32 vcc, 32, v60
	v_cndmask_b32_e32 v98, v217, v98, vcc
	v_cmp_ge_i32_e32 vcc, 1, v60
	v_cndmask_b32_e32 v115, v217, v115, vcc
	v_cmp_ge_i32_e32 vcc, 33, v60
	v_cndmask_b32_e32 v99, v217, v99, vcc
	v_cmp_ge_i32_e32 vcc, 2, v60
	v_cndmask_b32_e32 v116, v217, v116, vcc
	v_cmp_ge_i32_e32 vcc, 34, v60
	v_cndmask_b32_e32 v100, v217, v100, vcc
	v_cmp_ge_i32_e32 vcc, 3, v60
	v_cndmask_b32_e32 v117, v217, v117, vcc
	v_cmp_ge_i32_e32 vcc, 35, v60
	v_cndmask_b32_e32 v101, v217, v101, vcc
	v_cmp_ge_i32_e32 vcc, 8, v60
	v_cndmask_b32_e32 v118, v217, v118, vcc
	v_cmp_ge_i32_e32 vcc, 40, v60
	v_cndmask_b32_e32 v102, v217, v102, vcc
	v_cmp_ge_i32_e32 vcc, 9, v60
	v_cndmask_b32_e32 v119, v217, v119, vcc
	v_cmp_ge_i32_e32 vcc, 41, v60
	v_cndmask_b32_e32 v103, v217, v103, vcc
	v_cmp_ge_i32_e32 vcc, 10, v60
	v_cndmask_b32_e32 v120, v217, v120, vcc
	v_cmp_ge_i32_e32 vcc, 42, v60
	v_cndmask_b32_e32 v104, v217, v104, vcc
	v_cmp_ge_i32_e32 vcc, 11, v60
	v_cndmask_b32_e32 v121, v217, v121, vcc
	v_cmp_ge_i32_e32 vcc, 43, v60
	v_cndmask_b32_e32 v105, v217, v105, vcc
	v_cmp_ge_i32_e32 vcc, 16, v60
	v_cndmask_b32_e32 v122, v217, v122, vcc
	v_cmp_ge_i32_e32 vcc, 48, v60
	v_cndmask_b32_e32 v106, v217, v106, vcc
	v_cmp_ge_i32_e32 vcc, 17, v60
	v_cndmask_b32_e32 v123, v217, v123, vcc
	v_cmp_ge_i32_e32 vcc, 49, v60
	v_cndmask_b32_e32 v107, v217, v107, vcc
	v_cmp_ge_i32_e32 vcc, 18, v60
	v_cndmask_b32_e32 v124, v217, v124, vcc
	v_cmp_ge_i32_e32 vcc, 50, v60
	v_cndmask_b32_e32 v108, v217, v108, vcc
	v_cmp_ge_i32_e32 vcc, 19, v60
	v_cndmask_b32_e32 v125, v217, v125, vcc
	v_cmp_ge_i32_e32 vcc, 51, v60
	v_cndmask_b32_e32 v109, v217, v109, vcc
	v_cmp_ge_i32_e32 vcc, 24, v60
	v_cndmask_b32_e32 v126, v217, v126, vcc
	v_cmp_ge_i32_e32 vcc, 56, v60
	v_cndmask_b32_e32 v110, v217, v110, vcc
	v_cmp_ge_i32_e32 vcc, 25, v60
	v_cndmask_b32_e32 v127, v217, v127, vcc
	v_cmp_ge_i32_e32 vcc, 57, v60
	v_cndmask_b32_e32 v111, v217, v111, vcc
	v_cmp_ge_i32_e32 vcc, 26, v60
	v_cndmask_b32_e32 v128, v217, v128, vcc
	v_cmp_ge_i32_e32 vcc, 58, v60
	v_cndmask_b32_e32 v112, v217, v112, vcc
	v_cmp_ge_i32_e32 vcc, 27, v60
	v_cndmask_b32_e32 v129, v217, v129, vcc
	v_cmp_ge_i32_e32 vcc, 59, v60
	v_cndmask_b32_e32 v113, v217, v113, vcc
.Lmy_mk_e_b2:
.LBB0_503:
	v_add_f32_e32 v82, v82, v58
	s_mov_b64 s[70:71], 0
	s_and_saveexec_b64 s[44:45], s[40:41]
	s_cbranch_execz .LBB0_506
	v_max_f32_e32 v58, v115, v115
	v_max_f32_e32 v59, v114, v114
	v_max_f32_e32 v58, v59, v58
	v_max3_f32 v59, v116, v117, v99
	v_max3_f32 v58, v58, v98, v100
	v_max3_f32 v58, v58, v101, v118
	v_max3_f32 v59, v59, v120, v121
	v_max3_f32 v58, v58, v119, v102
	v_max3_f32 v59, v59, v104, v105
	v_max3_f32 v58, v58, v103, v122
	v_max3_f32 v59, v59, v124, v125
	v_max3_f32 v58, v58, v123, v106
	v_max3_f32 v59, v59, v108, v109
	v_max3_f32 v58, v58, v107, v126
	v_max3_f32 v59, v59, v128, v129
	v_max3_f32 v58, v58, v127, v110
	v_max3_f32 v59, v59, v112, v113
	v_max3_f32 v58, v58, v111, v59
	v_mov_b32_e32 v59, v58
	s_nop 1
	v_permlane32_swap_b32_e32 v58, v59
	v_max_f32_e32 v59, v59, v59
	v_max_f32_e32 v58, v58, v58
	v_max_f32_e32 v58, v58, v59
	v_cmp_lt_f32_e32 vcc, s84, v58
	s_cbranch_vccnz .LBB0_535

.LBB0_540:
	v_add_u32_e32 v83, s87, v232
	v_add_u32_e32 v255, 0xe800, v83
	ds_read_b64_tr_b16 v[84:85], v83 offset:24576
	ds_read_b64_tr_b16 v[86:87], v83 offset:25088
	s_waitcnt lgkmcnt(9)
	v_mfma_f32_32x32x16_bf16 v[66:81], v[174:177], v[2:5], v[66:81]
	v_add_f32_e32 v88, v114, v115
	v_add_f32_e32 v88, v116, v88
	v_add_f32_e32 v88, v117, v88
	v_add_f32_e32 v88, v118, v88
	v_add_f32_e32 v92, v119, v88
	v_cvt_pk_bf16_f32 v142, v114, v115
	v_cvt_pk_bf16_f32 v143, v116, v117
	ds_read_b64_tr_b16 v[88:89], v83 offset:28672
	ds_read_b64_tr_b16 v[90:91], v83 offset:29184
	s_waitcnt lgkmcnt(10)
	v_mfma_f32_32x32x16_bf16 v[50:65], v[170:173], v[2:5], v[50:65]
	v_add_f32_e32 v92, v120, v92
	v_add_f32_e32 v92, v121, v92
	v_add_f32_e32 v92, v122, v92
	v_add_f32_e32 v96, v123, v92
	v_cvt_pk_bf16_f32 v144, v118, v119
	v_cvt_pk_bf16_f32 v145, v120, v121
	ds_read_b64_tr_b16 v[92:93], v83 offset:25600
	ds_read_b64_tr_b16 v[94:95], v83 offset:26112
	s_waitcnt lgkmcnt(11)
	v_mfma_f32_32x32x16_bf16 v[66:81], v[166:169], v[6:9], v[66:81]
	v_add_f32_e32 v96, v124, v96
	v_add_f32_e32 v96, v125, v96
	v_add_f32_e32 v96, v126, v96
	v_add_f32_e32 v96, v127, v96
	v_cvt_pk_bf16_f32 v138, v122, v123
	v_cvt_pk_bf16_f32 v139, v124, v125
	ds_read_b64_tr_b16 v[114:115], v83 offset:29696
	ds_read_b64_tr_b16 v[116:117], v83 offset:30208
	s_waitcnt lgkmcnt(12)
	v_mfma_f32_32x32x16_bf16 v[50:65], v[162:165], v[6:9], v[50:65]
	v_add_f32_e32 v96, v128, v96
	v_add_f32_e32 v96, v129, v96
	v_add_f32_e32 v96, v98, v96
	v_add_f32_e32 v96, v99, v96
	v_cvt_pk_bf16_f32 v140, v126, v127
	v_cvt_pk_bf16_f32 v141, v128, v129
	ds_read_b64_tr_b16 v[118:119], v83 offset:26624
	ds_read_b64_tr_b16 v[120:121], v83 offset:27136
	s_waitcnt lgkmcnt(13)
	v_mfma_f32_32x32x16_bf16 v[66:81], v[158:161], v[10:13], v[66:81]
	v_add_f32_e32 v96, v100, v96
	v_add_f32_e32 v96, v101, v96
	v_add_f32_e32 v96, v102, v96
	v_add_f32_e32 v122, v103, v96
	v_cvt_pk_bf16_f32 v134, v98, v99
	v_cvt_pk_bf16_f32 v135, v100, v101
	ds_read_b64_tr_b16 v[96:97], v83 offset:30720
	ds_read_b64_tr_b16 v[98:99], v83 offset:31232
	s_waitcnt lgkmcnt(14)
	v_mfma_f32_32x32x16_bf16 v[50:65], v[154:157], v[10:13], v[50:65]
	v_add_f32_e32 v100, v104, v122
	v_add_f32_e32 v100, v105, v100
	v_add_f32_e32 v100, v106, v100
	v_add_f32_e32 v122, v107, v100
	v_cvt_pk_bf16_f32 v136, v102, v103
	v_cvt_pk_bf16_f32 v137, v104, v105
	ds_read_b64_tr_b16 v[100:101], v83 offset:27648
	ds_read_b64_tr_b16 v[102:103], v83 offset:28160
	s_waitcnt lgkmcnt(14)
	v_mfma_f32_32x32x16_bf16 v[66:81], v[150:153], v[14:17], v[66:81]
	v_add_f32_e32 v104, v108, v122
	v_add_f32_e32 v104, v109, v104
	v_add_f32_e32 v104, v110, v104
	v_add_f32_e32 v122, v111, v104
	v_cvt_pk_bf16_f32 v130, v106, v107
	v_cvt_pk_bf16_f32 v131, v108, v109
	ds_read_b64_tr_b16 v[104:105], v83 offset:31744
	ds_read_b64_tr_b16 v[106:107], v83 offset:32256
	v_mfma_f32_32x32x16_bf16 v[50:65], v[146:149], v[14:17], v[50:65]
	v_add_f32_e32 v83, v112, v122
	v_add_f32_e32 v83, v113, v83
	v_add_f32_e32 v83, 0, v83
	v_cvt_pk_bf16_f32 v132, v110, v111
	v_cvt_pk_bf16_f32 v133, v112, v113
	s_lshl_b32 s4, s4, 6
	s_sub_i32 s42, s4, 64
	v_or_b32_e32 v108, s42, v230
	v_sub_u32_e32 v108, v223, v108
	s_nop 0
	v_readfirstlane_b32 s43, v108
	s_cmp_gt_i32 s43, 66
	s_cbranch_scc1 .Lmy_mk_c_ls
	v_cmp_le_i32_e32 vcc, 0, v108
	v_cndmask_b32_e32 v66, v217, v66, vcc
	v_cmp_le_i32_e32 vcc, 32, v108
	v_cndmask_b32_e32 v50, v217, v50, vcc
	v_cmp_le_i32_e32 vcc, 1, v108
	v_cndmask_b32_e32 v67, v217, v67, vcc
	v_cmp_le_i32_e32 vcc, 33, v108
	v_cndmask_b32_e32 v51, v217, v51, vcc
	v_cmp_le_i32_e32 vcc, 2, v108
	v_cndmask_b32_e32 v68, v217, v68, vcc
	v_cmp_le_i32_e32 vcc, 34, v108
	v_cndmask_b32_e32 v52, v217, v52, vcc
	v_cmp_le_i32_e32 vcc, 3, v108
	v_cndmask_b32_e32 v69, v217, v69, vcc
	v_cmp_le_i32_e32 vcc, 35, v108
	v_cndmask_b32_e32 v53, v217, v53, vcc
	v_cmp_le_i32_e32 vcc, 8, v108
	v_cndmask_b32_e32 v70, v217, v70, vcc
	v_cmp_le_i32_e32 vcc, 40, v108
	v_cndmask_b32_e32 v54, v217, v54, vcc
	v_cmp_le_i32_e32 vcc, 9, v108
	v_cndmask_b32_e32 v71, v217, v71, vcc
	v_cmp_le_i32_e32 vcc, 41, v108
	v_cndmask_b32_e32 v55, v217, v55, vcc
	v_cmp_le_i32_e32 vcc, 10, v108
	v_cndmask_b32_e32 v72, v217, v72, vcc
	v_cmp_le_i32_e32 vcc, 42, v108
	v_cndmask_b32_e32 v56, v217, v56, vcc
	v_cmp_le_i32_e32 vcc, 11, v108
	v_cndmask_b32_e32 v73, v217, v73, vcc
	v_cmp_le_i32_e32 vcc, 43, v108
	v_cndmask_b32_e32 v57, v217, v57, vcc
	v_cmp_le_i32_e32 vcc, 16, v108
	v_cndmask_b32_e32 v74, v217, v74, vcc
	v_cmp_le_i32_e32 vcc, 48, v108
	v_cndmask_b32_e32 v58, v217, v58, vcc
	v_cmp_le_i32_e32 vcc, 17, v108
	v_cndmask_b32_e32 v75, v217, v75, vcc
	v_cmp_le_i32_e32 vcc, 49, v108
	v_cndmask_b32_e32 v59, v217, v59, vcc
	v_cmp_le_i32_e32 vcc, 18, v108
	v_cndmask_b32_e32 v76, v217, v76, vcc
	v_cmp_le_i32_e32 vcc, 50, v108
	v_cndmask_b32_e32 v60, v217, v60, vcc
	v_cmp_le_i32_e32 vcc, 19, v108
	v_cndmask_b32_e32 v77, v217, v77, vcc
	v_cmp_le_i32_e32 vcc, 51, v108
	v_cndmask_b32_e32 v61, v217, v61, vcc
	v_cmp_le_i32_e32 vcc, 24, v108
	v_cndmask_b32_e32 v78, v217, v78, vcc
	v_cmp_le_i32_e32 vcc, 56, v108
	v_cndmask_b32_e32 v62, v217, v62, vcc
	v_cmp_le_i32_e32 vcc, 25, v108
	v_cndmask_b32_e32 v79, v217, v79, vcc
	v_cmp_le_i32_e32 vcc, 57, v108
	v_cndmask_b32_e32 v63, v217, v63, vcc
	v_cmp_le_i32_e32 vcc, 26, v108
	v_cndmask_b32_e32 v80, v217, v80, vcc
	v_cmp_le_i32_e32 vcc, 58, v108
	v_cndmask_b32_e32 v64, v217, v64, vcc
	v_cmp_le_i32_e32 vcc, 27, v108
	v_cndmask_b32_e32 v81, v217, v81, vcc
	v_cmp_le_i32_e32 vcc, 59, v108
	v_cndmask_b32_e32 v65, v217, v65, vcc
; __device__ __forceinline__ void gmask(f32x16&p0,f32x16&p1,int kvb,int qrel,int hi,bool WIN){
;   const float NEG=-INFINITY; int kb=kvb+4*hi;
;   #pragma unroll
;   for(int r=0;r<16;++r){int kv=kb+(r&3)+8*(r>>2); if(kv>qrel)p0[r]=NEG; if(kv+32>qrel)p1[r]=NEG;
;     if(WIN){ if(kv<=qrel-128)p0[r]=NEG; if(kv+32<=qrel-128)p1[r]=NEG; } }
; }
.Lmy_mk_c_ls:
	s_and_b64 vcc, exec, s[38:39]
	s_cbranch_vccnz .Lmy_mk_e_ls
	s_cmp_lt_i32 s43, 0x61
	s_cbranch_scc1 .Lmy_mk_e_ls
	v_add_u32_e32 v109, 0xffffff81, v108
	v_cmp_ge_i32_e32 vcc, 0, v109
	v_cndmask_b32_e32 v66, v217, v66, vcc
	v_cmp_ge_i32_e32 vcc, 32, v109
	v_cndmask_b32_e32 v50, v217, v50, vcc
	v_cmp_ge_i32_e32 vcc, 1, v109
	v_cndmask_b32_e32 v67, v217, v67, vcc
	v_cmp_ge_i32_e32 vcc, 33, v109
	v_cndmask_b32_e32 v51, v217, v51, vcc
	v_cmp_ge_i32_e32 vcc, 2, v109
	v_cndmask_b32_e32 v68, v217, v68, vcc
	v_cmp_ge_i32_e32 vcc, 34, v109
	v_cndmask_b32_e32 v52, v217, v52, vcc
	v_cmp_ge_i32_e32 vcc, 3, v109
	v_cndmask_b32_e32 v69, v217, v69, vcc
	v_cmp_ge_i32_e32 vcc, 35, v109
	v_cndmask_b32_e32 v53, v217, v53, vcc
	v_cmp_ge_i32_e32 vcc, 8, v109
	v_cndmask_b32_e32 v70, v217, v70, vcc
	v_cmp_ge_i32_e32 vcc, 40, v109
	v_cndmask_b32_e32 v54, v217, v54, vcc
	v_cmp_ge_i32_e32 vcc, 9, v109
	v_cndmask_b32_e32 v71, v217, v71, vcc
	v_cmp_ge_i32_e32 vcc, 41, v109
	v_cndmask_b32_e32 v55, v217, v55, vcc
	v_cmp_ge_i32_e32 vcc, 10, v109
	v_cndmask_b32_e32 v72, v217, v72, vcc
	v_cmp_ge_i32_e32 vcc, 42, v109
	v_cndmask_b32_e32 v56, v217, v56, vcc
	v_cmp_ge_i32_e32 vcc, 11, v109
	v_cndmask_b32_e32 v73, v217, v73, vcc
	v_cmp_ge_i32_e32 vcc, 43, v109
	v_cndmask_b32_e32 v57, v217, v57, vcc
	v_cmp_ge_i32_e32 vcc, 16, v109
	v_cndmask_b32_e32 v74, v217, v74, vcc
	v_cmp_ge_i32_e32 vcc, 48, v109
	v_cndmask_b32_e32 v58, v217, v58, vcc
	v_cmp_ge_i32_e32 vcc, 17, v109
	v_cndmask_b32_e32 v75, v217, v75, vcc
	v_cmp_ge_i32_e32 vcc, 49, v109
	v_cndmask_b32_e32 v59, v217, v59, vcc
	v_cmp_ge_i32_e32 vcc, 18, v109
	v_cndmask_b32_e32 v76, v217, v76, vcc
	v_cmp_ge_i32_e32 vcc, 50, v109
	v_cndmask_b32_e32 v60, v217, v60, vcc
	v_cmp_ge_i32_e32 vcc, 19, v109
	v_cndmask_b32_e32 v77, v217, v77, vcc
	v_cmp_ge_i32_e32 vcc, 51, v109
	v_cndmask_b32_e32 v61, v217, v61, vcc
	v_cmp_ge_i32_e32 vcc, 24, v109
	v_cndmask_b32_e32 v78, v217, v78, vcc
	v_cmp_ge_i32_e32 vcc, 56, v109
	v_cndmask_b32_e32 v62, v217, v62, vcc
	v_cmp_ge_i32_e32 vcc, 25, v109
	v_cndmask_b32_e32 v79, v217, v79, vcc
	v_cmp_ge_i32_e32 vcc, 57, v109
	v_cndmask_b32_e32 v63, v217, v63, vcc
	v_cmp_ge_i32_e32 vcc, 26, v109
	v_cndmask_b32_e32 v80, v217, v80, vcc
	v_cmp_ge_i32_e32 vcc, 58, v109
	v_cndmask_b32_e32 v64, v217, v64, vcc
	v_cmp_ge_i32_e32 vcc, 27, v109
	v_cndmask_b32_e32 v81, v217, v81, vcc
	v_cmp_ge_i32_e32 vcc, 59, v109
	v_cndmask_b32_e32 v65, v217, v65, vcc
.Lmy_mk_e_ls:
.LBB0_604:
	v_add_f32_e32 v122, v82, v83
	s_mov_b64 s[38:39], 0
	s_and_saveexec_b64 s[42:43], s[40:41]
	s_cbranch_execz .LBB0_607
	v_max_f32_e32 v82, v67, v67
	v_max_f32_e32 v83, v66, v66
	v_max_f32_e32 v82, v83, v82
	v_max3_f32 v83, v68, v69, v51
	v_max3_f32 v82, v82, v50, v52
	v_max3_f32 v82, v82, v53, v70
	v_max3_f32 v83, v83, v72, v73
	v_max3_f32 v82, v82, v71, v54
	v_max3_f32 v83, v83, v56, v57
	v_max3_f32 v82, v82, v55, v74
	v_max3_f32 v83, v83, v76, v77
	v_max3_f32 v82, v82, v75, v58
	v_max3_f32 v83, v83, v60, v61
	v_max3_f32 v82, v82, v59, v78
	v_max3_f32 v83, v83, v80, v81
	v_max3_f32 v82, v82, v79, v62
	v_max3_f32 v83, v83, v64, v65
	v_max3_f32 v82, v82, v63, v83
	v_mov_b32_e32 v83, v82
	s_nop 1
	v_permlane32_swap_b32_e32 v82, v83
	v_max_f32_e32 v83, v83, v83
	v_max_f32_e32 v82, v82, v82
	v_max_f32_e32 v82, v82, v83
	v_cmp_lt_f32_e32 vcc, s84, v82
	s_cbranch_vccnz .LBB0_623
